# v193 + map-0 waves skip the output-store drain at the next unit's first tile (flag, counted vmcnt(8))
# speedup vs baseline: 1.0003x; 1.0003x over previous
.LBB0_1112:
	s_cmp_lt_i32 s28, 11
	s_cselect_b64 s[2:3], -1, 0
	s_and_b64 s[2:3], s[2:3], s[0:1]
	s_andn2_b64 vcc, exec, s[2:3]
	s_cbranch_vccnz .LBB0_1140
	s_cmpk_gt_i32 s76, 0x3ff
	s_cbranch_scc1 .LBB0_1139
	s_add_u32 s72, s24, 0x1e200000
	s_addc_u32 s73, s25, 0
	s_add_u32 s74, s24, 0x20200000
	s_addc_u32 s75, s25, 0
	s_add_u32 s4, s24, 0x16a00000
	s_addc_u32 s5, s25, 0
	s_add_u32 s8, s24, 0x22200000
	s_addc_u32 s9, s25, 0
	s_lshr_b32 s11, s77, 7
	s_lshr_b32 s1, s77, 5
	s_bfe_u32 s0, s77, 0x10006
	s_and_b32 s26, s1, 12
	s_lshl_b32 s1, s11, 15
	s_lshl_b32 s11, s11, 12
	s_add_i32 s79, s11, 0
	s_lshl_b32 s11, s0, 10
	v_readlane_b32 s59, v250, 2
	s_lshr_b32 s7, s77, 8
	s_add_i32 s79, s79, s11
	s_lshl_b32 s11, s59, 10
	s_add_i32 s54, 0, 0x10000
	s_bfe_u32 s10, s77, 0x20006
	s_add_i32 s27, 0, 0x20000
	s_add_i32 s80, s54, s11
	s_lshl_b32 s11, s7, 10
	s_lshl_b32 s78, s10, 4
	s_lshl_b32 s50, s7, 7
	s_lshl_b32 s55, s7, 4
	s_add_i32 s81, s27, s11
	s_lshl_b32 s11, s10, 14
	s_cmp_lt_u32 s10, 2
	s_mov_b32 s10, 0x8000
	s_cselect_b32 s10, s10, 0x10000
	s_add_i32 s11, s11, 0
	s_add_i32 s56, s11, s10
	s_cmp_eq_u32 s7, 1
	s_cselect_b64 s[10:11], -1, 0
	s_add_u32 s14, s24, 0x22204000
	s_addc_u32 s15, s25, 0
	s_cmpk_lt_u32 s77, 0x100
	s_cselect_b64 s[16:17], -1, 0
	s_bfe_u32 s92, s76, 0x30003
	s_lshl_b32 s7, s92, 22
	s_add_u32 s7, s74, s7
	s_addc_u32 s30, s75, 0
	s_lshl_b32 s31, s76, 5
	s_and_b32 s51, s31, 0x1800
	s_lshl_b32 s31, s51, 1
	s_add_u32 s48, s7, s31
	s_addc_u32 s49, s30, 0
	s_lshl_b32 s7, s51, 12
	s_add_u32 s7, s72, s7
	v_and_b32_e32 v0, 0x300, v226
	s_addc_u32 s40, s73, 0
	s_lshl_b32 s57, s92, 9
	v_add_u32_e32 v0, s57, v0
	s_movk_i32 s30, 0xff
	v_and_or_b32 v0, v226, s30, v0
	v_lshlrev_b32_e32 v0, 2, v0
	global_load_dword v1, v0, s[8:9]
	v_lshrrev_b32_e32 v32, 5, v227
	v_lshl_or_b32 v0, s0, 1, v32
	v_and_b32_e32 v2, 31, v226
	v_bitop3_b32 v2, v0, v2, s26 bitop3:0x36
	v_lshlrev_b32_e32 v0, 12, v0
	v_lshlrev_b32_e32 v33, 4, v2
	v_lshrrev_b32_e32 v34, 3, v227
	v_or3_b32 v132, v0, s1, v33
	v_lshl_or_b32 v0, s59, 3, v34
	v_lshrrev_b32_e32 v2, 1, v0
	v_xor_b32_e32 v2, v2, v226
	v_lshlrev_b32_e32 v2, 4, v2
	s_add_u32 s52, s7, s57
	v_and_b32_e32 v35, 0x70, v2
	s_addc_u32 s53, s40, 0
	v_lshl_or_b32 v134, v0, 14, v35
	v_mov_b32_e32 v0, 0
	s_add_u32 s7, s18, s57
	v_lshl_add_u32 v151, v226, 2, s27
	v_mov_b32_e32 v135, v0
	s_addc_u32 s27, s19, 0
	s_and_b32 s26, s77, 0xffffff00
	v_mov_b32_e32 v133, v0
	v_lshl_add_u64 v[4:5], s[48:49], 0, v[134:135]
	s_mov_b64 s[30:31], 0x300000
	s_mov_b64 s[34:35], 0x200000
	s_mov_b64 s[36:37], 0x100000
	s_add_u32 s26, s7, s26
	v_and_b32_e32 v2, 48, v227
	v_mov_b32_e32 v3, v0
	v_lshl_add_u64 v[20:21], v[4:5], 0, s[30:31]
	v_lshl_add_u64 v[22:23], v[4:5], 0, s[34:35]
	v_lshl_add_u64 v[24:25], v[4:5], 0, s[36:37]
	v_lshl_add_u64 v[4:5], s[52:53], 0, v[132:133]
	s_mov_b64 s[40:41], 0x24000
	s_mov_b64 s[42:43], 0x20000
	s_mov_b64 s[46:47], 0x4000
	s_addc_u32 s27, s27, 0
	s_and_b32 s7, s76, 7
	v_lshl_add_u64 v[26:27], v[4:5], 0, s[40:41]
	v_lshl_add_u64 v[28:29], v[4:5], 0, s[42:43]
	v_lshl_add_u64 v[30:31], v[4:5], 0, s[46:47]
	v_lshl_add_u64 v[4:5], s[26:27], 0, v[2:3]
	s_xor_b32 s26, s7, 31
	s_ashr_i32 s27, s76, 8
	s_xor_b32 s57, s7, 23
	s_or_b32 s58, s7, 8
	s_cmp_eq_u32 s27, 2
	s_cselect_b32 s57, s57, s58
	s_cmp_eq_u32 s27, 1
	s_cselect_b32 s7, s7, s57
	s_cmpk_lt_u32 s76, 0x100
	s_cselect_b32 s7, s26, s7
	s_lshl_b32 s26, s7, 6
	s_or_b32 s87, s26, s78
	v_and_b32_e32 v150, 15, v226
	s_add_i32 s93, s87, s51
	v_or_b32_e32 v6, s93, v150
	v_mov_b32_e32 v7, v0
	v_lshlrev_b64 v[6:7], 12, v[6:7]
	v_lshl_add_u64 v[16:17], v[4:5], 0, v[6:7]
	s_mov_b32 m0, s79
	s_add_i32 s77, s79, 0x800
	global_load_dwordx4 v[4:7], v[16:17], off
	s_add_i32 s82, s79, 0x4000
	s_add_i32 s83, s79, 0x4800
	s_add_i32 s84, s80, 0x2000
	s_add_i32 s85, s80, 0x4000
	s_add_i32 s86, s80, 0x6000
	v_lshl_add_u64 v[136:137], s[20:21], 0, v[2:3]
	s_add_i32 s69, s7, 1
	s_lshl_b32 s7, s59, 17
	s_lshl_b32 s0, s0, 13
	s_or_b32 s0, s1, s0
	s_mov_b32 s51, 0
	v_lshl_add_u32 v152, v227, 4, s56
	v_lshl_add_u32 v157, v150, 7, s54
	v_mov_b32_e32 v139, v0
	v_mov_b32_e32 v141, v0
	s_waitcnt vmcnt(0)
	ds_write_b32 v151, v1
	global_load_dwordx4 v[8:11], v[16:17], off offset:64
	global_load_dwordx4 v[12:15], v[16:17], off offset:128
	s_nop 0
	global_load_dwordx4 v[16:19], v[16:17], off offset:192
	v_lshrrev_b32_e32 v1, 4, v227
	global_load_lds_dwordx4 v132, s[52:53]
	s_mov_b32 m0, s77
	v_bitop3_b32 v2, s55, v150, v1 bitop3:0x36
	global_load_lds_dwordx4 v[30:31], off
	s_mov_b32 m0, s82
	v_lshlrev_b32_e32 v153, 4, v2
	global_load_lds_dwordx4 v[28:29], off
	s_mov_b32 m0, s83
	s_mov_b64 s[20:21], 0x40000
	global_load_lds_dwordx4 v[26:27], off
	s_mov_b32 m0, s80
	s_mov_b64 s[56:57], 0x60000
	global_load_lds_dwordx4 v134, s[48:49]
	s_mov_b32 m0, s84
	s_mov_b64 s[58:59], 0x64000
	global_load_lds_dwordx4 v[24:25], off
	s_mov_b32 m0, s85
	v_lshrrev_b32_e32 v24, 1, v226
	global_load_lds_dwordx4 v[22:23], off
	s_mov_b32 m0, s86
	v_or_b32_e32 v23, s55, v1
	global_load_lds_dwordx4 v[20:21], off
	v_bitop3_b32 v2, v23, v150, 4 bitop3:0x36
	v_lshlrev_b32_e32 v154, 4, v2
	v_bitop3_b32 v2, v23, v150, 8 bitop3:0x36
	v_lshlrev_b32_e32 v21, 1, v226
	v_and_b32_e32 v22, 3, v226
	v_bfe_u32 v25, v226, 1, 3
	v_lshlrev_b32_e32 v155, 4, v2
	v_bitop3_b32 v2, v23, v150, 12 bitop3:0x36
	v_lshlrev_b32_e32 v20, 3, v1
	v_and_or_b32 v21, v21, 24, v22
	v_lshlrev_b32_e32 v22, 2, v1
	v_lshlrev_b32_e32 v156, 4, v2
	v_bitop3_b32 v2, v1, v24, 7 bitop3:0x78
	v_bitop3_b32 v1, v1, v25, 4 bitop3:0x36
	v_lshlrev_b32_e32 v159, 4, v1
	v_lshlrev_b32_e32 v1, 14, v34
	v_or3_b32 v138, s7, v1, v35
	v_lshlrev_b32_e32 v1, 12, v32
	v_or3_b32 v140, s0, v1, v33
	v_mbcnt_lo_u32_b32 v1, -1, 0
	v_lshlrev_b32_e32 v158, 4, v2
	v_lshl_add_u32 v160, v21, 9, 0
	v_sub_u32_e32 v161, v20, v150
	s_mov_b64 s[54:55], 0x44000
	s_mov_b64 s[60:61], 0x80
	s_mov_b64 s[62:63], 0x100080
	s_mov_b64 s[64:65], 0x200080
	s_mov_b64 s[66:67], 0x300080
	s_lshl_b32 s68, s50, 1
	v_lshlrev_b32_e32 v142, 1, v20
	v_mov_b32_e32 v162, 0x3727c5ac
	s_mov_b32 s88, 0xf800000
	v_mov_b32_e32 v163, 0x260
	s_mov_b32 s89, 0x3f24fd5c
	v_lshlrev_b32_e32 v144, 1, v22
	v_mbcnt_hi_u32_b32 v164, -1, v1
	s_mov_b32 s95, 0
	s_branch .LBB0_1116

.LBB0_1117:
	s_cmp_eq_u32 s95, 0
	s_cbranch_scc1 .Latt_w_full
	s_mov_b32 s95, 0
	s_waitcnt vmcnt(8)
	s_branch .Latt_w_done

.Latt_w_done:
	s_waitcnt lgkmcnt(0)
	s_barrier
	s_and_b32 s92, s70, 1
	s_add_i32 s70, s70, 1
	s_lshl_b32 s71, s92, 15
	v_add_u32_e32 v2, s71, v160
	v_add_u32_e32 v3, v2, v153
	v_add_u32_e32 v124, v2, v154
	v_add_u32_e32 v125, v2, v155
	v_add_u32_e32 v2, v2, v156
	ds_read_b128 v[84:87], v3
	ds_read_b128 v[88:91], v3 offset:2048
	ds_read_b128 v[92:95], v124
	ds_read_b128 v[96:99], v124 offset:2048
	ds_read_b128 v[100:103], v125
	ds_read_b128 v[104:107], v125 offset:2048
	ds_read_b128 v[108:111], v2
	ds_read_b128 v[112:115], v2 offset:2048
	ds_read_b128 v[116:119], v3 offset:16384
	ds_read_b128 v[166:169], v3 offset:18432
	ds_read_b128 v[120:123], v124 offset:16384
	ds_read_b128 v[170:173], v124 offset:18432
	ds_read_b128 v[174:177], v125 offset:16384
	ds_read_b128 v[178:181], v125 offset:18432
	ds_read_b128 v[182:185], v2 offset:16384
	ds_read_b128 v[186:189], v2 offset:18432
	s_cmp_lt_i32 s70, s69
	s_cbranch_scc0 .Latt_k_done
	s_xor_b32 s0, s71, 0x8000
	s_add_i32 s1, s79, s0
	s_add_u32 s54, s54, 0x40000
	s_addc_u32 s55, s55, 0
	s_mov_b32 m0, s1
	s_add_u32 s58, s54, 0x4000
	global_load_lds_dwordx4 v140, s[54:55]
	s_addc_u32 s59, s55, 0
	s_add_i32 m0, s1, 0x800
	s_nop 0
	global_load_lds_dwordx4 v140, s[58:59]
	s_add_u32 s58, s54, 0x20000
	s_addc_u32 s59, s55, 0
	s_add_i32 m0, s1, 0x4000
	s_nop 0
	global_load_lds_dwordx4 v140, s[58:59]
	s_add_u32 s58, s54, 0x24000
	s_addc_u32 s59, s55, 0
	s_add_i32 m0, s1, 0x4800
	s_nop 0
	global_load_lds_dwordx4 v140, s[58:59]

.LBB0_1137:
	s_waitcnt lgkmcnt(0)
	s_barrier
	s_andn2_b64 vcc, exec, s[16:17]
	s_cbranch_vccnz .LBB0_1115
	v_div_scale_f32 v3, s[0:1], v2, v2, 1.0
	v_rcp_f32_e32 v84, v3
	v_div_scale_f32 v86, vcc, 1.0, v2, 1.0
	s_lshl_b32 s50, s90, 9
	v_fma_f32 v87, -v3, v84, 1.0
	v_fmac_f32_e32 v84, v87, v84
	v_mul_f32_e32 v90, v86, v84
	v_fma_f32 v87, -v3, v90, v86
	v_fmac_f32_e32 v90, v87, v84
	v_fma_f32 v3, -v3, v90, v86
	v_div_fmas_f32 v3, v3, v84, v90
	ds_read_b128 v[166:169], v152
	ds_read_b128 v[170:173], v152 offset:1024
	ds_read_b128 v[174:177], v152 offset:2048
	ds_read_b128 v[178:181], v152 offset:3072
	ds_read_b128 v[182:185], v152 offset:4096
	ds_read_b128 v[186:189], v152 offset:5120
	ds_read_b128 v[190:193], v152 offset:6144
	ds_read_b128 v[194:197], v152 offset:7168
	ds_read_b128 v[198:201], v152 offset:8192
	ds_read_b128 v[202:205], v152 offset:9216
	ds_read_b128 v[206:209], v152 offset:10240
	ds_read_b128 v[210:213], v152 offset:11264
	ds_read_b128 v[214:217], v152 offset:12288
	ds_read_b128 v[218:221], v152 offset:13312
	ds_read_b128 v[86:89], v152 offset:14336
	ds_read_b128 v[90:93], v152 offset:15360
	v_div_fixup_f32 v84, v3, v2, 1.0
	v_mov_b32_e32 v145, v0
	s_waitcnt lgkmcnt(14)
	v_xor_b32_e32 v3, 0x80000000, v169
	v_xor_b32_e32 v2, 0x80000000, v168
	v_pk_fma_f32 v[80:81], v[80:81], v[84:85], v[166:167] op_sel_hi:[1,0,1] neg_lo:[0,0,1] neg_hi:[0,0,1]
	v_pk_fma_f32 v[82:83], v[82:83], v[84:85], v[2:3] op_sel_hi:[1,0,1]
	v_pk_mul_f32 v[166:167], v[80:81], v[80:81]
	v_pk_mul_f32 v[2:3], v[82:83], v[82:83]
	s_nop 0
	v_pk_mov_b32 v[168:169], v[166:167], v[2:3] op_sel:[1,0]
	v_mov_b32_e32 v167, v3
	v_pk_fma_f32 v[2:3], v[76:77], v[84:85], v[170:171] op_sel_hi:[1,0,1] neg_lo:[0,0,1] neg_hi:[0,0,1]
	v_xor_b32_e32 v77, 0x80000000, v173
	v_xor_b32_e32 v76, 0x80000000, v172
	v_pk_fma_f32 v[76:77], v[78:79], v[84:85], v[76:77] op_sel_hi:[1,0,1]
	v_pk_mul_f32 v[170:171], v[2:3], v[2:3]
	v_pk_mul_f32 v[78:79], v[76:77], v[76:77]
	v_pk_add_f32 v[94:95], v[168:169], v[166:167]
	v_pk_mov_b32 v[172:173], v[170:171], v[78:79] op_sel:[1,0]
	v_mov_b32_e32 v171, v79
	v_pk_add_f32 v[78:79], v[172:173], v[170:171]
	v_pk_add_f32 v[78:79], v[78:79], v[78:79] op_sel:[0,1] op_sel_hi:[1,0]
	s_waitcnt lgkmcnt(12)
	v_xor_b32_e32 v177, 0x80000000, v177
	v_xor_b32_e32 v176, 0x80000000, v176
	v_pk_fma_f32 v[72:73], v[72:73], v[84:85], v[174:175] op_sel_hi:[1,0,1] neg_lo:[0,0,1] neg_hi:[0,0,1]
	v_xor_b32_e32 v175, 0x80000000, v181
	v_xor_b32_e32 v174, 0x80000000, v180
	v_pk_fma_f32 v[68:69], v[68:69], v[84:85], v[178:179] op_sel_hi:[1,0,1] neg_lo:[0,0,1] neg_hi:[0,0,1]
	v_pk_fma_f32 v[74:75], v[74:75], v[84:85], v[176:177] op_sel_hi:[1,0,1]
	v_pk_fma_f32 v[70:71], v[70:71], v[84:85], v[174:175] op_sel_hi:[1,0,1]
	v_mul_f32_e32 v176, v68, v68
	v_mul_f32_e32 v177, v69, v69
	v_pk_add_f32 v[174:175], v[94:95], v[94:95] op_sel:[0,1] op_sel_hi:[1,0]
	v_mov_b32_e32 v79, v177
	v_mov_b32_e32 v175, v176
	v_pk_add_f32 v[78:79], v[174:175], v[78:79]
	v_mul_f32_e32 v174, v73, v73
	v_mul_f32_e32 v180, v70, v70
	v_pk_fma_f32 v[178:179], v[72:73], v[72:73], v[174:175] op_sel_hi:[1,1,0]
	v_mul_f32_e32 v174, v75, v75
	v_mov_b32_e32 v179, v180
	v_pk_fma_f32 v[180:181], v[74:75], v[74:75], v[174:175] op_sel_hi:[1,1,0]
	v_mul_f32_e32 v96, v71, v71
	v_mov_b32_e32 v181, v96
	v_pk_add_f32 v[178:179], v[178:179], v[180:181]
	s_nop 0
	v_pk_add_f32 v[78:79], v[78:79], v[178:179]
	s_waitcnt lgkmcnt(10)
	v_pk_fma_f32 v[64:65], v[64:65], v[84:85], v[182:183] op_sel_hi:[1,0,1] neg_lo:[0,0,1] neg_hi:[0,0,1]
	v_xor_b32_e32 v183, 0x80000000, v185
	v_xor_b32_e32 v182, 0x80000000, v184
	v_pk_fma_f32 v[66:67], v[66:67], v[84:85], v[182:183] op_sel_hi:[1,0,1]
	v_pk_mul_f32 v[184:185], v[64:65], v[64:65]
	v_pk_mul_f32 v[182:183], v[66:67], v[66:67]
	v_xor_b32_e32 v189, 0x80000000, v189
	v_pk_mov_b32 v[94:95], v[184:185], v[182:183] op_sel:[1,0]
	v_mov_b32_e32 v185, v183
	v_pk_add_f32 v[94:95], v[94:95], v[184:185]
	v_xor_b32_e32 v188, 0x80000000, v188
	v_pk_fma_f32 v[62:63], v[62:63], v[84:85], v[188:189] op_sel_hi:[1,0,1]
	v_pk_fma_f32 v[60:61], v[60:61], v[84:85], v[186:187] op_sel_hi:[1,0,1] neg_lo:[0,0,1] neg_hi:[0,0,1]
	s_waitcnt lgkmcnt(8)
	v_pk_fma_f32 v[56:57], v[56:57], v[84:85], v[190:191] op_sel_hi:[1,0,1] neg_lo:[0,0,1] neg_hi:[0,0,1]
	v_xor_b32_e32 v193, 0x80000000, v193
	v_xor_b32_e32 v192, 0x80000000, v192
	v_mul_f32_e32 v190, v56, v56
	v_pk_add_f32 v[78:79], v[78:79], v[78:79] op_sel:[0,1] op_sel_hi:[1,0]
	v_pk_fma_f32 v[58:59], v[58:59], v[84:85], v[192:193] op_sel_hi:[1,0,1]
	v_mul_f32_e32 v192, v57, v57
	v_mov_b32_e32 v79, v190
	v_pk_add_f32 v[190:191], v[94:95], v[94:95] op_sel:[0,1] op_sel_hi:[1,0]
	v_mul_f32_e32 v193, v58, v58
	v_mov_b32_e32 v191, v192
	v_pk_add_f32 v[78:79], v[78:79], v[190:191]
	v_mul_f32_e32 v190, v61, v61
	v_pk_fma_f32 v[190:191], v[60:61], v[60:61], v[190:191] op_sel_hi:[1,1,0]
	v_mul_f32_e32 v192, v63, v63
	v_mul_f32_e32 v96, v59, v59
	v_mov_b32_e32 v191, v193
	v_pk_fma_f32 v[192:193], v[62:63], v[62:63], v[192:193] op_sel_hi:[1,1,0]
	v_pk_fma_f32 v[52:53], v[52:53], v[84:85], v[194:195] op_sel_hi:[1,0,1] neg_lo:[0,0,1] neg_hi:[0,0,1]
	v_mov_b32_e32 v193, v96
	v_pk_add_f32 v[190:191], v[190:191], v[192:193]
	s_nop 0
	v_pk_add_f32 v[78:79], v[78:79], v[190:191]
	v_xor_b32_e32 v191, 0x80000000, v197
	v_xor_b32_e32 v190, 0x80000000, v196
	v_pk_fma_f32 v[54:55], v[54:55], v[84:85], v[190:191] op_sel_hi:[1,0,1]
	v_pk_mul_f32 v[196:197], v[52:53], v[52:53]
	v_pk_mul_f32 v[194:195], v[54:55], v[54:55]
	v_pk_mov_b32 v[94:95], v[196:197], v[194:195] op_sel:[1,0]
	v_mov_b32_e32 v197, v195
	v_pk_add_f32 v[94:95], v[94:95], v[196:197]
	s_waitcnt lgkmcnt(6)
	v_pk_fma_f32 v[48:49], v[48:49], v[84:85], v[198:199] op_sel_hi:[1,0,1] neg_lo:[0,0,1] neg_hi:[0,0,1]
	v_xor_b32_e32 v201, 0x80000000, v201
	v_xor_b32_e32 v200, 0x80000000, v200
	v_pk_add_f32 v[78:79], v[78:79], v[78:79] op_sel:[0,1] op_sel_hi:[1,0]
	v_xor_b32_e32 v199, 0x80000000, v205
	v_xor_b32_e32 v198, 0x80000000, v204
	v_pk_fma_f32 v[44:45], v[44:45], v[84:85], v[202:203] op_sel_hi:[1,0,1] neg_lo:[0,0,1] neg_hi:[0,0,1]
	v_pk_fma_f32 v[46:47], v[46:47], v[84:85], v[198:199] op_sel_hi:[1,0,1]
	v_mul_f32_e32 v198, v44, v44
	v_pk_fma_f32 v[50:51], v[50:51], v[84:85], v[200:201] op_sel_hi:[1,0,1]
	v_mul_f32_e32 v200, v45, v45
	v_mov_b32_e32 v79, v198
	v_pk_add_f32 v[198:199], v[94:95], v[94:95] op_sel:[0,1] op_sel_hi:[1,0]
	v_mul_f32_e32 v201, v46, v46
	v_mov_b32_e32 v199, v200
	v_pk_add_f32 v[78:79], v[78:79], v[198:199]
	v_mul_f32_e32 v198, v49, v49
	v_pk_fma_f32 v[202:203], v[48:49], v[48:49], v[198:199] op_sel_hi:[1,1,0]
	v_mul_f32_e32 v198, v51, v51
	v_mov_b32_e32 v203, v201
	v_pk_fma_f32 v[204:205], v[50:51], v[50:51], v[198:199] op_sel_hi:[1,1,0]
	v_mul_f32_e32 v96, v47, v47
	v_mov_b32_e32 v205, v96
	v_pk_add_f32 v[202:203], v[202:203], v[204:205]
	s_nop 0
	v_pk_add_f32 v[78:79], v[78:79], v[202:203]
	s_waitcnt lgkmcnt(4)
	v_pk_fma_f32 v[40:41], v[40:41], v[84:85], v[206:207] op_sel_hi:[1,0,1] neg_lo:[0,0,1] neg_hi:[0,0,1]
	v_xor_b32_e32 v207, 0x80000000, v209
	v_xor_b32_e32 v206, 0x80000000, v208
	v_pk_fma_f32 v[42:43], v[42:43], v[84:85], v[206:207] op_sel_hi:[1,0,1]
	v_pk_mul_f32 v[208:209], v[40:41], v[40:41]
	v_pk_mul_f32 v[206:207], v[42:43], v[42:43]
	v_xor_b32_e32 v213, 0x80000000, v213
	v_pk_mov_b32 v[94:95], v[208:209], v[206:207] op_sel:[1,0]
	v_mov_b32_e32 v209, v207
	v_pk_add_f32 v[94:95], v[94:95], v[208:209]
	v_xor_b32_e32 v212, 0x80000000, v212
	v_pk_fma_f32 v[38:39], v[38:39], v[84:85], v[212:213] op_sel_hi:[1,0,1]
	v_pk_fma_f32 v[36:37], v[36:37], v[84:85], v[210:211] op_sel_hi:[1,0,1] neg_lo:[0,0,1] neg_hi:[0,0,1]
	s_waitcnt lgkmcnt(2)
	v_pk_fma_f32 v[32:33], v[32:33], v[84:85], v[214:215] op_sel_hi:[1,0,1] neg_lo:[0,0,1] neg_hi:[0,0,1]
	v_xor_b32_e32 v217, 0x80000000, v217
	v_xor_b32_e32 v216, 0x80000000, v216
	v_mul_f32_e32 v214, v32, v32
	v_pk_add_f32 v[78:79], v[78:79], v[78:79] op_sel:[0,1] op_sel_hi:[1,0]
	v_pk_fma_f32 v[34:35], v[34:35], v[84:85], v[216:217] op_sel_hi:[1,0,1]
	v_mul_f32_e32 v216, v33, v33
	v_mov_b32_e32 v79, v214
	v_pk_add_f32 v[214:215], v[94:95], v[94:95] op_sel:[0,1] op_sel_hi:[1,0]
	v_mul_f32_e32 v217, v34, v34
	v_mov_b32_e32 v215, v216
	v_pk_add_f32 v[78:79], v[78:79], v[214:215]
	v_mul_f32_e32 v214, v37, v37
	v_pk_fma_f32 v[214:215], v[36:37], v[36:37], v[214:215] op_sel_hi:[1,1,0]
	v_mul_f32_e32 v216, v39, v39
	v_mul_f32_e32 v96, v35, v35
	v_mov_b32_e32 v215, v217
	v_pk_fma_f32 v[216:217], v[38:39], v[38:39], v[216:217] op_sel_hi:[1,1,0]
	v_pk_fma_f32 v[28:29], v[28:29], v[84:85], v[218:219] op_sel_hi:[1,0,1] neg_lo:[0,0,1] neg_hi:[0,0,1]
	v_mov_b32_e32 v217, v96
	v_pk_add_f32 v[214:215], v[214:215], v[216:217]
	s_nop 0
	v_pk_add_f32 v[78:79], v[78:79], v[214:215]
	v_xor_b32_e32 v215, 0x80000000, v221
	v_xor_b32_e32 v214, 0x80000000, v220
	v_pk_fma_f32 v[30:31], v[30:31], v[84:85], v[214:215] op_sel_hi:[1,0,1]
	v_pk_mul_f32 v[218:219], v[30:31], v[30:31]
	v_pk_mul_f32 v[220:221], v[28:29], v[28:29]
	v_pk_add_f32 v[78:79], v[78:79], v[78:79] op_sel:[0,1] op_sel_hi:[1,0]
	v_pk_mov_b32 v[94:95], v[220:221], v[218:219] op_sel:[1,0]
	v_mov_b32_e32 v221, v219
	v_pk_add_f32 v[94:95], v[94:95], v[220:221]
	s_waitcnt lgkmcnt(0)
	v_xor_b32_e32 v89, 0x80000000, v89
	v_xor_b32_e32 v88, 0x80000000, v88
	v_pk_fma_f32 v[26:27], v[26:27], v[84:85], v[88:89] op_sel_hi:[1,0,1]
	v_pk_fma_f32 v[24:25], v[24:25], v[84:85], v[86:87] op_sel_hi:[1,0,1] neg_lo:[0,0,1] neg_hi:[0,0,1]
	global_load_dwordx4 v[86:89], v[136:137], off
	global_load_dwordx4 v[166:169], v[136:137], off offset:64
	global_load_dwordx4 v[170:173], v[136:137], off offset:128
	global_load_dwordx4 v[174:177], v[136:137], off offset:192
	global_load_dwordx4 v[178:181], v[136:137], off offset:256
	global_load_dwordx4 v[182:185], v[136:137], off offset:320
	global_load_dwordx4 v[186:189], v[136:137], off offset:384
	global_load_dwordx4 v[190:193], v[136:137], off offset:448
	global_load_dwordx4 v[194:197], v[136:137], off offset:512
	global_load_dwordx4 v[198:201], v[136:137], off offset:576
	global_load_dwordx4 v[202:205], v[136:137], off offset:640
	global_load_dwordx4 v[206:209], v[136:137], off offset:704
	global_load_dwordx4 v[210:213], v[136:137], off offset:768
	global_load_dwordx4 v[214:217], v[136:137], off offset:832
	global_load_dwordx4 v[218:221], v[136:137], off offset:896
	global_load_dwordx4 v[222:225], v[136:137], off offset:960
	v_xor_b32_e32 v93, 0x80000000, v93
	v_xor_b32_e32 v92, 0x80000000, v92
	v_pk_fma_f32 v[20:21], v[20:21], v[84:85], v[90:91] op_sel_hi:[1,0,1] neg_lo:[0,0,1] neg_hi:[0,0,1]
	v_pk_fma_f32 v[22:23], v[22:23], v[84:85], v[92:93] op_sel_hi:[1,0,1]
	v_mul_f32_e32 v84, v20, v20
	v_mul_f32_e32 v92, v21, v21
	v_pk_add_f32 v[90:91], v[94:95], v[94:95] op_sel:[0,1] op_sel_hi:[1,0]
	v_mov_b32_e32 v79, v84
	v_mov_b32_e32 v91, v92
	v_mul_f32_e32 v84, v25, v25
	v_mul_f32_e32 v93, v22, v22
	v_pk_add_f32 v[78:79], v[78:79], v[90:91]
	v_pk_fma_f32 v[90:91], v[24:25], v[24:25], v[84:85] op_sel_hi:[1,1,0]
	v_mul_f32_e32 v84, v27, v27
	v_mul_f32_e32 v96, v23, v23
	v_mov_b32_e32 v91, v93
	v_pk_fma_f32 v[92:93], v[26:27], v[26:27], v[84:85] op_sel_hi:[1,1,0]
	s_waitcnt vmcnt(0)
	v_pk_mul_f32 v[80:81], v[80:81], v[86:87]
	v_mov_b32_e32 v93, v96
	v_pk_add_f32 v[90:91], v[90:91], v[92:93]
	v_pk_mul_f32 v[82:83], v[82:83], v[88:89]
	v_pk_add_f32 v[78:79], v[78:79], v[90:91]
	s_nop 0
	v_add_f32_e32 v78, v78, v79
	ds_bpermute_b32 v1, v1, v78
	s_waitcnt lgkmcnt(0)
	v_add_f32_e32 v1, v78, v1
	ds_bpermute_b32 v78, v85, v1
	s_waitcnt lgkmcnt(0)
	v_add_f32_e32 v1, v1, v78
	v_fmamk_f32 v1, v1, 0x3b800000, v162
	v_mul_f32_e32 v78, 0x4f800000, v1
	v_cmp_gt_f32_e32 vcc, s88, v1
	s_nop 1
	v_cndmask_b32_e32 v1, v1, v78, vcc
	v_sqrt_f32_e32 v78, v1
	s_nop 0
	v_add_u32_e32 v79, -1, v78
	v_fma_f32 v84, -v79, v78, v1
	v_cmp_ge_f32_e64 s[0:1], 0, v84
	v_add_u32_e32 v84, 1, v78
	s_nop 0
	v_cndmask_b32_e64 v79, v78, v79, s[0:1]
	v_fma_f32 v78, -v84, v78, v1
	v_cmp_lt_f32_e64 s[0:1], 0, v78
	s_nop 1
	v_cndmask_b32_e64 v78, v79, v84, s[0:1]
	v_mul_f32_e32 v79, 0x37800000, v78
	v_cndmask_b32_e32 v78, v78, v79, vcc
	v_cmp_class_f32_e32 vcc, v1, v163
	s_nop 1
	v_cndmask_b32_e32 v1, v78, v1, vcc
	v_div_scale_f32 v78, s[0:1], v1, v1, s89
	v_rcp_f32_e32 v79, v78
	s_nop 0
	v_fma_f32 v84, -v78, v79, 1.0
	v_fmac_f32_e32 v79, v84, v79
	v_div_scale_f32 v84, vcc, s89, v1, s89
	v_mul_f32_e32 v85, v84, v79
	v_fma_f32 v90, -v78, v85, v84
	v_fmac_f32_e32 v85, v90, v79
	v_fma_f32 v78, -v78, v85, v84
	v_div_fmas_f32 v78, v78, v79, v85
	v_div_fixup_f32 v84, v78, v1, s89
	v_lshrrev_b32_e32 v78, 5, v227
	v_mul_u32_u24_e32 v96, 0x210, v78
	v_add_u32_e32 v78, s91, v78
	v_mov_b32_e32 v79, v0
	v_lshlrev_b64 v[78:79], 12, v[78:79]
	v_lshl_add_u64 v[78:79], s[4:5], 0, v[78:79]
	v_lshl_add_u64 v[78:79], v[78:79], 0, s[50:51]
	v_and_b32_e32 v98, 31, v227
	v_lshlrev_b32_e32 v98, 4, v98
	v_mov_b32_e32 v99, v0
	v_add_u32_e32 v96, v96, v98
	v_lshlrev_b32_e32 v100, 4, v227
	v_sub_u32_e32 v100, v152, v100
	v_add_u32_e32 v96, v100, v96
	v_lshl_add_u64 v[78:79], v[78:79], 0, v[98:99]
	v_and_b32_e32 v97, 15, v227
	v_mul_u32_u24_e32 v97, 0x210, v97
	v_lshrrev_b32_e32 v98, 4, v227
	v_lshl_add_u32 v97, v98, 3, v97
	v_add_u32_e32 v97, v100, v97
	v_pk_mul_f32 v[80:81], v[80:81], v[84:85] op_sel_hi:[1,0]
	v_pk_mul_f32 v[82:83], v[82:83], v[84:85] op_sel_hi:[1,0]
	v_cvt_pk_bf16_f32 v80, v80, v81
	s_nop 0
	v_cvt_pk_bf16_f32 v81, v82, v83
	ds_write_b64 v97, v[80:81]
	v_pk_mul_f32 v[2:3], v[2:3], v[166:167]
	v_pk_mul_f32 v[76:77], v[76:77], v[168:169]
	v_pk_mul_f32 v[2:3], v[2:3], v[84:85] op_sel_hi:[1,0]
	v_pk_mul_f32 v[76:77], v[76:77], v[84:85] op_sel_hi:[1,0]
	v_cvt_pk_bf16_f32 v2, v2, v3
	s_nop 0
	v_cvt_pk_bf16_f32 v3, v76, v77
	ds_write_b64 v97, v[2:3] offset:32
	v_pk_mul_f32 v[2:3], v[72:73], v[170:171]
	v_pk_mul_f32 v[72:73], v[74:75], v[172:173]
	v_pk_mul_f32 v[2:3], v[2:3], v[84:85] op_sel_hi:[1,0]
	v_pk_mul_f32 v[72:73], v[72:73], v[84:85] op_sel_hi:[1,0]
	v_cvt_pk_bf16_f32 v2, v2, v3
	s_nop 0
	v_cvt_pk_bf16_f32 v3, v72, v73
	ds_write_b64 v97, v[2:3] offset:64
	v_pk_mul_f32 v[2:3], v[68:69], v[174:175]
	v_pk_mul_f32 v[68:69], v[70:71], v[176:177]
	v_pk_mul_f32 v[2:3], v[84:85], v[2:3] op_sel_hi:[0,1]
	v_pk_mul_f32 v[68:69], v[84:85], v[68:69] op_sel_hi:[0,1]
	v_cvt_pk_bf16_f32 v2, v2, v3
	v_cvt_pk_bf16_f32 v3, v68, v69
	ds_write_b64 v97, v[2:3] offset:96
	v_pk_mul_f32 v[2:3], v[64:65], v[178:179]
	v_pk_mul_f32 v[64:65], v[66:67], v[180:181]
	v_pk_mul_f32 v[2:3], v[84:85], v[2:3] op_sel_hi:[0,1]
	v_pk_mul_f32 v[64:65], v[84:85], v[64:65] op_sel_hi:[0,1]
	v_cvt_pk_bf16_f32 v2, v2, v3
	v_cvt_pk_bf16_f32 v3, v64, v65
	ds_write_b64 v97, v[2:3] offset:128
	v_pk_mul_f32 v[2:3], v[60:61], v[182:183]
	v_pk_mul_f32 v[60:61], v[62:63], v[184:185]
	v_pk_mul_f32 v[2:3], v[84:85], v[2:3] op_sel_hi:[0,1]
	v_pk_mul_f32 v[60:61], v[84:85], v[60:61] op_sel_hi:[0,1]
	v_cvt_pk_bf16_f32 v2, v2, v3
	v_cvt_pk_bf16_f32 v3, v60, v61
	ds_write_b64 v97, v[2:3] offset:160
	v_pk_mul_f32 v[2:3], v[56:57], v[186:187]
	v_pk_mul_f32 v[56:57], v[58:59], v[188:189]
	v_pk_mul_f32 v[2:3], v[84:85], v[2:3] op_sel_hi:[0,1]
	v_pk_mul_f32 v[56:57], v[84:85], v[56:57] op_sel_hi:[0,1]
	v_cvt_pk_bf16_f32 v2, v2, v3
	v_cvt_pk_bf16_f32 v3, v56, v57
	ds_write_b64 v97, v[2:3] offset:192
	v_pk_mul_f32 v[2:3], v[52:53], v[190:191]
	v_pk_mul_f32 v[52:53], v[54:55], v[192:193]
	v_pk_mul_f32 v[2:3], v[84:85], v[2:3] op_sel_hi:[0,1]
	v_pk_mul_f32 v[52:53], v[84:85], v[52:53] op_sel_hi:[0,1]
	v_cvt_pk_bf16_f32 v2, v2, v3
	v_cvt_pk_bf16_f32 v3, v52, v53
	ds_write_b64 v97, v[2:3] offset:224
	v_pk_mul_f32 v[2:3], v[48:49], v[194:195]
	v_pk_mul_f32 v[48:49], v[50:51], v[196:197]
	v_pk_mul_f32 v[2:3], v[84:85], v[2:3] op_sel_hi:[0,1]
	v_pk_mul_f32 v[48:49], v[84:85], v[48:49] op_sel_hi:[0,1]
	v_cvt_pk_bf16_f32 v2, v2, v3
	v_cvt_pk_bf16_f32 v3, v48, v49
	ds_write_b64 v97, v[2:3] offset:256
	v_pk_mul_f32 v[2:3], v[44:45], v[198:199]
	v_pk_mul_f32 v[44:45], v[46:47], v[200:201]
	v_pk_mul_f32 v[2:3], v[84:85], v[2:3] op_sel_hi:[0,1]
	v_pk_mul_f32 v[44:45], v[84:85], v[44:45] op_sel_hi:[0,1]
	v_cvt_pk_bf16_f32 v2, v2, v3
	v_cvt_pk_bf16_f32 v3, v44, v45
	ds_write_b64 v97, v[2:3] offset:288
	v_pk_mul_f32 v[2:3], v[40:41], v[202:203]
	v_pk_mul_f32 v[40:41], v[42:43], v[204:205]
	v_pk_mul_f32 v[2:3], v[84:85], v[2:3] op_sel_hi:[0,1]
	v_pk_mul_f32 v[40:41], v[84:85], v[40:41] op_sel_hi:[0,1]
	v_cvt_pk_bf16_f32 v2, v2, v3
	v_cvt_pk_bf16_f32 v3, v40, v41
	ds_write_b64 v97, v[2:3] offset:320
	v_pk_mul_f32 v[2:3], v[36:37], v[206:207]
	v_pk_mul_f32 v[36:37], v[38:39], v[208:209]
	v_pk_mul_f32 v[2:3], v[84:85], v[2:3] op_sel_hi:[0,1]
	v_pk_mul_f32 v[36:37], v[84:85], v[36:37] op_sel_hi:[0,1]
	v_cvt_pk_bf16_f32 v2, v2, v3
	v_cvt_pk_bf16_f32 v3, v36, v37
	ds_write_b64 v97, v[2:3] offset:352
	v_pk_mul_f32 v[2:3], v[32:33], v[210:211]
	v_pk_mul_f32 v[32:33], v[34:35], v[212:213]
	v_pk_mul_f32 v[2:3], v[84:85], v[2:3] op_sel_hi:[0,1]
	v_pk_mul_f32 v[32:33], v[84:85], v[32:33] op_sel_hi:[0,1]
	v_cvt_pk_bf16_f32 v2, v2, v3
	v_cvt_pk_bf16_f32 v3, v32, v33
	ds_write_b64 v97, v[2:3] offset:384
	v_pk_mul_f32 v[2:3], v[28:29], v[214:215]
	v_pk_mul_f32 v[28:29], v[30:31], v[216:217]
	v_pk_mul_f32 v[2:3], v[84:85], v[2:3] op_sel_hi:[0,1]
	v_pk_mul_f32 v[28:29], v[84:85], v[28:29] op_sel_hi:[0,1]
	v_cvt_pk_bf16_f32 v2, v2, v3
	v_cvt_pk_bf16_f32 v3, v28, v29
	ds_write_b64 v97, v[2:3] offset:416
	v_pk_mul_f32 v[2:3], v[24:25], v[218:219]
	v_pk_mul_f32 v[24:25], v[26:27], v[220:221]
	v_pk_mul_f32 v[2:3], v[84:85], v[2:3] op_sel_hi:[0,1]
	v_pk_mul_f32 v[24:25], v[84:85], v[24:25] op_sel_hi:[0,1]
	v_cvt_pk_bf16_f32 v2, v2, v3
	v_cvt_pk_bf16_f32 v3, v24, v25
	ds_write_b64 v97, v[2:3] offset:448
	v_pk_mul_f32 v[2:3], v[20:21], v[222:223]
	v_pk_mul_f32 v[20:21], v[22:23], v[224:225]
	v_pk_mul_f32 v[2:3], v[84:85], v[2:3] op_sel_hi:[0,1]
	v_pk_mul_f32 v[20:21], v[84:85], v[20:21] op_sel_hi:[0,1]
	v_cvt_pk_bf16_f32 v2, v2, v3
	v_cvt_pk_bf16_f32 v3, v20, v21
	ds_write_b64 v97, v[2:3] offset:480
	s_mov_b32 s0, 0x2000
	s_mov_b32 s1, 0
	s_waitcnt lgkmcnt(0)
	ds_read_b128 v[98:101], v96
	ds_read_b128 v[102:105], v96 offset:1056
	ds_read_b128 v[106:109], v96 offset:2112
	ds_read_b128 v[110:113], v96 offset:3168
	ds_read_b128 v[114:117], v96 offset:4224
	ds_read_b128 v[118:121], v96 offset:5280
	ds_read_b128 v[122:125], v96 offset:6336
	ds_read_b128 v[126:129], v96 offset:7392
	s_waitcnt lgkmcnt(7)
	global_store_dwordx4 v[78:79], v[98:101], off
	v_lshl_add_u64 v[78:79], v[78:79], 0, s[0:1]
	s_waitcnt lgkmcnt(6)
	global_store_dwordx4 v[78:79], v[102:105], off
	v_lshl_add_u64 v[78:79], v[78:79], 0, s[0:1]
	s_waitcnt lgkmcnt(5)
	global_store_dwordx4 v[78:79], v[106:109], off
	v_lshl_add_u64 v[78:79], v[78:79], 0, s[0:1]
	s_waitcnt lgkmcnt(4)
	global_store_dwordx4 v[78:79], v[110:113], off
	v_lshl_add_u64 v[78:79], v[78:79], 0, s[0:1]
	s_waitcnt lgkmcnt(3)
	global_store_dwordx4 v[78:79], v[114:117], off
	v_lshl_add_u64 v[78:79], v[78:79], 0, s[0:1]
	s_waitcnt lgkmcnt(2)
	global_store_dwordx4 v[78:79], v[118:121], off
	v_lshl_add_u64 v[78:79], v[78:79], 0, s[0:1]
	s_waitcnt lgkmcnt(1)
	global_store_dwordx4 v[78:79], v[122:125], off
	v_lshl_add_u64 v[78:79], v[78:79], 0, s[0:1]
	s_waitcnt lgkmcnt(0)
	global_store_dwordx4 v[78:79], v[126:129], off
	s_mov_b32 s95, 1
	s_branch .LBB0_1115
